# split XCD-local barrier: arrive at phase end, wait + L1 invalidate + closing workgroup barrier in the next phase's prologue (next phase's scalar setup overlaps the barrier latency)
# speedup vs baseline: 1.0105x; 1.0105x over previous
.LBB0_29:
	s_lshl_b32 s0, s12, 5
	s_add_i32 s6, s0, s13
	s_cmp_lg_u32 s14, 0
	s_cselect_b64 s[0:1], -1, 0
	s_and_b64 s[0:1], s[0:1], exec
	s_cselect_b32 s8, s6, s3
	s_lshl_b32 s0, s8, 6
	s_and_b32 s0, s0, 0xfffff800
	s_add_i32 s1, s0, 0x800
	s_cmp_lg_u32 s14, 0
	s_cselect_b64 s[6:7], -1, 0
	s_and_b64 s[6:7], s[6:7], exec
	s_cselect_b32 s98, s1, 0x4000
	s_lshl_b32 s10, s62, 3
	s_cmp_lg_u32 s14, 0
	s_cselect_b64 s[6:7], -1, 0
	s_and_b64 s[6:7], s[6:7], exec
	s_cselect_b32 s64, 0x100, s10
	s_lshl_b32 s1, s8, 4
	s_and_b32 s1, s1, 0xfffffe00
	s_add_i32 s3, s1, 0x200
	s_cmp_lg_u32 s14, 0
	s_cselect_b64 s[6:7], -1, 0
	s_and_b64 s[6:7], s[6:7], exec
	s_cselect_b32 s99, s3, 0x1000
	s_lshl_b32 s3, s13, 3
	s_add_i32 s3, s3, s12
	s_cmp_lg_u32 s14, 0
	s_cselect_b64 s[6:7], -1, 0
	v_writelane_b32 v236, s6, 8
	s_mov_b32 s36, 2.0
	s_mov_b32 s88, 0x41900000
	v_writelane_b32 v236, s7, 9
	s_and_b64 s[6:7], s[6:7], exec
	s_cselect_b32 s7, s3, s2
	s_lshl_b32 s9, s8, 3
	s_add_u32 s2, s60, 0x5300000
	s_addc_u32 s3, s61, 0
	v_writelane_b32 v236, s2, 10
	s_mov_b32 s96, 0x41a00000
	s_mov_b32 s44, 0x42480000
	v_writelane_b32 v236, s3, 11
	s_add_u32 s2, s60, 0x7300000
	s_addc_u32 s3, s61, 0
	s_add_u32 s90, s60, 0xd300000
	s_addc_u32 s91, s61, 0
	s_add_u32 s92, s60, 0xf300000
	s_addc_u32 s93, s61, 0
	s_add_u32 s94, s60, 0x9300000
	v_writelane_b32 v236, s2, 12
	s_addc_u32 s95, s61, 0
	s_mov_b32 s84, 0x42000000
	v_writelane_b32 v236, s3, 13
	s_add_u32 s2, s60, 0x100000
	s_addc_u32 s3, s61, 0
	v_writelane_b32 v236, s2, 14
	v_mbcnt_lo_u32_b32 v0, -1, 0
	v_mov_b32_e32 v97, 0
	v_writelane_b32 v236, s3, 15
	s_add_u32 s2, s74, 0xb000
	s_addc_u32 s3, s75, 0
	v_writelane_b32 v236, s2, 16
	v_mov_b32_e32 v153, 0x358637bd
	v_mov_b32_e32 v154, 0x260
	v_writelane_b32 v236, s3, 17
	s_add_u32 s2, s60, 0x3d80000
	s_addc_u32 s3, s61, 0
	v_writelane_b32 v236, s2, 18
	s_mov_b32 s37, 0x40400000
	s_mov_b32 s89, 0x41980000
	v_writelane_b32 v236, s3, 19
	s_add_u32 s2, s60, 0x2200000
	s_addc_u32 s3, s61, 0
	v_writelane_b32 v236, s2, 20
	s_mov_b32 s97, 0x41a80000
	s_mov_b32 s45, 0x424c0000
	v_writelane_b32 v236, s3, 21
	s_add_u32 s2, s74, 0x9000
	s_addc_u32 s3, s75, 0
	v_writelane_b32 v236, s2, 22
	s_mov_b32 s85, 0x42040000
	v_mov_b32_e32 v155, 1
	v_writelane_b32 v236, s3, 23
	s_add_u32 s2, s60, 0x5100000
	s_addc_u32 s3, s61, 0
	v_writelane_b32 v236, s2, 24
	v_mbcnt_hi_u32_b32 v156, -1, v0
	v_mov_b32_e32 v157, 0x42800000
	v_writelane_b32 v236, s3, 25
	s_add_u32 s2, s60, 0x4f00000
	s_addc_u32 s3, s61, 0
	v_writelane_b32 v236, s2, 26
	v_mov_b32_e32 v158, 0xff800000
	s_nop 0
	v_writelane_b32 v236, s3, 27
	s_add_u32 s2, s74, 0x7000
	s_addc_u32 s3, s75, 0
	v_writelane_b32 v236, s2, 28
	s_nop 1
	v_writelane_b32 v236, s3, 29
	s_add_u32 s2, s60, 0x3800000
	s_addc_u32 s3, s61, 0
	v_writelane_b32 v236, s2, 30
	s_nop 1
	v_writelane_b32 v236, s3, 31
	s_add_u32 s2, s60, 0x1700000
	s_addc_u32 s3, s61, 0
	s_add_u32 s20, s60, 0xb300000
	v_writelane_b32 v236, s2, 32
	s_addc_u32 s21, s61, 0
	s_nop 0
	v_writelane_b32 v236, s3, 33
	s_add_u32 s2, s60, 0x4d00000
	s_addc_u32 s3, s61, 0
	v_writelane_b32 v236, s2, 34
	s_nop 1
	v_writelane_b32 v236, s3, 35
	s_add_u32 s2, s60, 0x4b00000
	s_addc_u32 s3, s61, 0
	v_writelane_b32 v236, s2, 36
	s_nop 1
	v_writelane_b32 v236, s3, 37
	s_add_u32 s2, s74, 0x5000
	s_addc_u32 s3, s75, 0
	v_writelane_b32 v236, s2, 38
	s_nop 1
	v_writelane_b32 v236, s3, 39
	s_add_u32 s2, s60, 0x3280000
	s_addc_u32 s3, s61, 0
	v_writelane_b32 v236, s2, 40
	s_nop 1
	v_writelane_b32 v236, s3, 41
	s_add_u32 s2, s60, 0xc00000
	s_addc_u32 s3, s61, 0
	v_writelane_b32 v236, s2, 42
	s_nop 1
	v_writelane_b32 v236, s3, 43
	s_add_u32 s2, s74, 0x3000
	s_addc_u32 s3, s75, 0
	v_writelane_b32 v236, s2, 44
	s_nop 1
	v_writelane_b32 v236, s3, 45
	s_add_u32 s2, s60, 0x4900000
	s_addc_u32 s3, s61, 0
	v_writelane_b32 v236, s2, 46
	s_nop 1
	v_writelane_b32 v236, s3, 47
	s_add_u32 s2, s60, 0x4300000
	s_addc_u32 s3, s61, 0
	v_writelane_b32 v236, s2, 48
	s_nop 1
	v_writelane_b32 v236, s3, 49
	s_add_u32 s2, s74, 0x1000
	s_addc_u32 s3, s75, 0
	v_writelane_b32 v236, s2, 50
	s_nop 1
	v_writelane_b32 v236, s3, 51
	s_add_u32 s2, s60, 0x2d00000
	s_addc_u32 s3, s61, 0
	v_writelane_b32 v236, s2, 52
	s_nop 1
	v_writelane_b32 v236, s3, 53
	s_add_u32 s2, s74, 0x2000
	s_addc_u32 s3, s75, 0
	v_writelane_b32 v236, s2, 54
	s_cmp_lg_u64 s[74:75], 0
	s_nop 0
	v_writelane_b32 v236, s3, 55
	s_cselect_b64 s[2:3], -1, 0
	v_writelane_b32 v236, s2, 56
	s_cmpk_eq_i32 s62, 0x100
	s_nop 0
	v_writelane_b32 v236, s3, 57
	s_cselect_b64 s[2:3], -1, 0
	v_writelane_b32 v236, s2, 58
	s_cmpk_lg_i32 s62, 0x100
	s_nop 0
	v_writelane_b32 v236, s3, 59
	s_cselect_b64 s[2:3], -1, 0
	v_writelane_b32 v236, s2, 60
	s_nop 1
	v_writelane_b32 v236, s3, 61
	s_add_u32 s2, s72, 0xb00000
	s_addc_u32 s3, s73, 0
	v_writelane_b32 v236, s2, 62
	s_nop 1
	v_writelane_b32 v236, s3, 63
	s_add_u32 s2, s70, 0x1600000
	s_addc_u32 s3, s71, 0
	v_writelane_b32 v235, s2, 0
	v_readlane_b32 s24, v236, 0
	v_readlane_b32 s30, v236, 6
	v_writelane_b32 v235, s3, 1
	s_add_u32 s2, s74, 0x4000
	s_addc_u32 s3, s75, 0
	v_writelane_b32 v235, s2, 2
	v_readlane_b32 s31, v236, 7
	v_readlane_b32 s25, v236, 1
	v_writelane_b32 v235, s3, 3
	s_add_u32 s2, s74, 0x8000
	s_addc_u32 s3, s75, 0
	v_writelane_b32 v235, s2, 4
	v_readlane_b32 s26, v236, 2
	v_readlane_b32 s27, v236, 3
	v_writelane_b32 v235, s3, 5
	s_add_u32 s2, s72, 0x1600000
	s_addc_u32 s3, s73, 0
	v_writelane_b32 v235, s2, 6
	v_readlane_b32 s28, v236, 4
	v_readlane_b32 s29, v236, 5
	v_writelane_b32 v235, s3, 7
	s_add_u32 s2, s70, 0x2c00000
	s_addc_u32 s3, s71, 0
	v_writelane_b32 v235, s2, 8
	s_mov_b32 s24, 0x40c00000
	s_mov_b32 s26, 0x42400000
	v_writelane_b32 v235, s3, 9
	s_add_u32 s2, s74, 0x6000
	s_addc_u32 s3, s75, 0
	v_writelane_b32 v235, s2, 10
	s_cmp_lg_u64 s[82:83], 0
	s_mov_b32 s28, 0x42180000
	v_writelane_b32 v235, s3, 11
	s_cselect_b64 s[2:3], -1, 0
	v_writelane_b32 v235, s2, 12
	s_mov_b32 s25, 0x40e00000
	s_mov_b32 s27, 0x42440000
	v_writelane_b32 v235, s3, 13
	s_add_u32 s2, s72, 0x2100000
	s_addc_u32 s3, s73, 0
	v_writelane_b32 v235, s2, 14
	s_mov_b32 s29, 0x421c0000
	s_nop 0
	v_writelane_b32 v235, s3, 15
	s_add_u32 s2, s70, 0x4200000
	s_addc_u32 s3, s71, 0
	v_writelane_b32 v235, s2, 16
	s_nop 1
	v_writelane_b32 v235, s3, 17
	s_add_u32 s2, s74, 0xa000
	s_addc_u32 s3, s75, 0
	v_writelane_b32 v235, s2, 18
	s_cmp_lg_u64 s[30:31], 0
	s_mov_b32 s30, 0x41800000
	v_writelane_b32 v235, s3, 19
	s_cselect_b64 s[2:3], -1, 0
	v_writelane_b32 v235, s2, 20
	s_mov_b32 s31, 0x41880000
	s_nop 0
	v_writelane_b32 v235, s3, 21
	s_add_u32 s2, s60, 0x12c00000
	v_writelane_b32 v235, s2, 22
	s_addc_u32 s2, s61, 0
	s_cmp_eq_u64 s[68:69], 0
	v_writelane_b32 v235, s2, 23
	s_cselect_b64 s[2:3], -1, 0
	s_cmp_lg_u64 s[68:69], 0
	s_cselect_b64 s[14:15], -1, 0
	v_writelane_b32 v235, s14, 24
	s_cmpk_lt_i32 s8, 0x100
	s_nop 0
	v_writelane_b32 v235, s15, 25
	v_writelane_b32 v235, s8, 26
	s_cselect_b64 s[14:15], -1, 0
	v_writelane_b32 v235, s14, 27
	s_and_b32 s6, s9, 0xf8
	s_or_b32 s1, s1, s6
	v_writelane_b32 v235, s15, 28
	v_writelane_b32 v235, s1, 29
	s_or_b32 s0, s0, s6
	v_writelane_b32 v235, s0, 30
	s_ashr_i32 s0, s7, 31
	v_writelane_b32 v235, s0, 31
	s_lshr_b32 s0, s0, 29
	s_add_i32 s0, s7, s0
	s_ashr_i32 s1, s0, 3
	s_and_b32 s0, s0, -8
	s_sub_i32 s8, s7, s0
	s_ashr_i32 s0, s62, 31
	v_writelane_b32 v235, s1, 32
	s_cmpk_gt_i32 s7, 0x7f
	v_writelane_b32 v235, s0, 33
	s_cselect_b64 s[0:1], -1, 0
	v_writelane_b32 v235, s0, 34
	s_nop 1
	v_writelane_b32 v235, s1, 35
	s_lshl_b32 s0, s7, 3
	s_addk_i32 s0, 0xfc00
	s_add_u32 s14, s60, 0x12b00200
	s_addc_u32 s15, s61, 0
	s_add_u32 s52, s60, 0x12b00400
	s_addc_u32 s53, s61, 0
	s_add_u32 s54, s60, 0x12b00500
	s_addc_u32 s55, s61, 0
	s_add_u32 s66, s60, 0x12b00600
	s_addc_u32 s67, s61, 0
	s_add_u32 s16, s60, 0x12b00700
	s_addc_u32 s17, s61, 0
	s_add_u32 s18, s60, 0x12b00800
	s_addc_u32 s19, s61, 0
	s_add_u32 s22, s60, 0x12b00900
	v_writelane_b32 v235, s7, 36
	s_addc_u32 s23, s61, 0
	v_writelane_b32 v235, s0, 37
	s_add_u32 s0, s60, 0x12b00a00
	s_addc_u32 s1, s61, 0
	v_writelane_b32 v235, s0, 38
	s_nop 1
	v_writelane_b32 v235, s1, 39
	s_add_u32 s0, s60, 0x12b00b00
	s_addc_u32 s1, s61, 0
	v_writelane_b32 v235, s0, 40
	s_nop 1
	v_writelane_b32 v235, s1, 41
	s_add_u32 s0, s60, 0x12b00c00
	s_addc_u32 s1, s61, 0
	v_writelane_b32 v235, s0, 42
	s_nop 1
	v_writelane_b32 v235, s1, 43
	s_add_u32 s0, s60, 0x12b00d00
	s_addc_u32 s1, s61, 0
	v_writelane_b32 v235, s0, 44
	s_nop 1
	v_writelane_b32 v235, s1, 45
	s_add_u32 s0, s60, 0x12b00e00
	s_addc_u32 s1, s61, 0
	v_writelane_b32 v235, s0, 46
	s_nop 1
	v_writelane_b32 v235, s1, 47
	s_add_u32 s0, s60, 0x12b00f00
	s_addc_u32 s1, s61, 0
	v_writelane_b32 v235, s0, 48
	s_nop 1
	v_writelane_b32 v235, s1, 49
	s_add_u32 s0, s60, 0x12b01000
	s_addc_u32 s1, s61, 0
	v_writelane_b32 v235, s0, 50
	s_nop 1
	v_writelane_b32 v235, s1, 51
	s_add_u32 s0, s60, 0x12b01100
	s_addc_u32 s1, s61, 0
	v_writelane_b32 v235, s0, 52
	s_nop 1
	v_writelane_b32 v235, s1, 53
	s_add_u32 s0, s60, 0x12b01200
	s_addc_u32 s1, s61, 0
	v_writelane_b32 v235, s0, 54
	s_nop 1
	v_writelane_b32 v235, s1, 55
	s_add_u32 s0, s60, 0x12b01300
	s_addc_u32 s1, s61, 0
	v_writelane_b32 v235, s0, 56
	s_cmp_eq_u32 s50, 15
	s_nop 0
	v_writelane_b32 v235, s1, 57
	s_cselect_b64 s[0:1], -1, 0
	v_writelane_b32 v235, s0, 58
	s_cmp_eq_u32 s50, 14
	s_nop 0
	v_writelane_b32 v235, s1, 59
	s_cselect_b64 s[0:1], -1, 0
	v_writelane_b32 v235, s0, 60
	s_cmp_eq_u32 s50, 13
	s_nop 0
	v_writelane_b32 v235, s1, 61
	s_cselect_b64 s[0:1], -1, 0
	v_writelane_b32 v235, s0, 62
	s_cmp_eq_u32 s50, 12
	s_nop 0
	v_writelane_b32 v235, s1, 63
	s_cselect_b64 s[0:1], -1, 0
	v_writelane_b32 v234, s0, 0
	s_cmp_eq_u32 s50, 11
	s_nop 0
	v_writelane_b32 v234, s1, 1
	s_cselect_b64 s[0:1], -1, 0
	v_writelane_b32 v234, s0, 2
	s_cmp_eq_u32 s50, 10
	s_nop 0
	v_writelane_b32 v234, s1, 3
	s_cselect_b64 s[0:1], -1, 0
	v_writelane_b32 v234, s0, 4
	s_cmp_eq_u32 s50, 9
	s_nop 0
	v_writelane_b32 v234, s1, 5
	s_cselect_b64 s[0:1], -1, 0
	v_writelane_b32 v234, s0, 6
	s_cmp_eq_u32 s50, 8
	s_nop 0
	v_writelane_b32 v234, s1, 7
	s_cselect_b64 s[0:1], -1, 0
	v_writelane_b32 v234, s0, 8
	s_cmp_eq_u32 s50, 7
	s_nop 0
	v_writelane_b32 v234, s1, 9
	s_cselect_b64 s[0:1], -1, 0
	v_writelane_b32 v234, s0, 10
	s_cmp_eq_u32 s50, 6
	s_nop 0
	v_writelane_b32 v234, s1, 11
	s_cselect_b64 s[0:1], -1, 0
	v_writelane_b32 v234, s0, 12
	s_cmp_eq_u32 s50, 5
	s_nop 0
	v_writelane_b32 v234, s1, 13
	s_cselect_b64 s[0:1], -1, 0
	v_writelane_b32 v234, s0, 14
	s_cmp_eq_u32 s50, 4
	s_nop 0
	v_writelane_b32 v234, s1, 15
	s_cselect_b64 s[0:1], -1, 0
	v_writelane_b32 v234, s0, 16
	s_cmp_eq_u32 s50, 3
	s_nop 0
	v_writelane_b32 v234, s1, 17
	s_cselect_b64 s[0:1], -1, 0
	v_writelane_b32 v234, s0, 18
	s_cmp_eq_u32 s50, 2
	s_nop 0
	v_writelane_b32 v234, s1, 19
	s_cselect_b64 s[0:1], -1, 0
	v_writelane_b32 v234, s0, 20
	s_cmp_eq_u32 s50, 1
	s_nop 0
	v_writelane_b32 v234, s1, 21
	s_cselect_b64 s[0:1], -1, 0
	v_writelane_b32 v234, s0, 22
	s_cmp_eq_u32 s50, 0
	s_nop 0
	v_writelane_b32 v234, s1, 23
	s_cselect_b64 s[0:1], -1, 0
	v_writelane_b32 v234, s0, 24
	s_nop 1
	v_writelane_b32 v234, s1, 25
	s_lshl_b32 s0, s50, 8
	s_add_u32 s0, s4, s0
	s_addc_u32 s1, s5, 0
	s_add_u32 s6, s0, 0x1400
	s_addc_u32 s7, s1, 0
	v_writelane_b32 v234, s6, 26
	s_add_u32 s0, s0, 0x2400
	s_addc_u32 s1, s1, 0
	v_writelane_b32 v234, s7, 27
	v_writelane_b32 v234, s0, 28
	s_mov_b64 s[50:51], s[14:15]
	s_mov_b32 s14, 4.0
	v_writelane_b32 v234, s1, 29
	s_add_u32 s0, s60, 0x12b03400
	s_addc_u32 s1, s61, 0
	v_writelane_b32 v234, s0, 30
	s_mov_b32 s15, 0x40a00000
	s_nop 0
	v_writelane_b32 v234, s1, 31
	s_add_u32 s0, s60, 0x12b03500
	s_addc_u32 s1, s61, 0
	s_lshl_b32 s6, s12, 6
	v_writelane_b32 v234, s0, 32
	s_add_i32 s46, s6, 0x1000
	s_mov_b64 s[12:13], 0x80
	v_writelane_b32 v234, s1, 33
	s_lshl_b64 s[0:1], s[46:47], 2
	s_add_u32 s0, s4, s0
	s_addc_u32 s1, s5, s1
	v_writelane_b32 v234, s0, 34
	s_add_i32 s46, s6, 0x1400
	s_nop 0
	v_writelane_b32 v234, s1, 35
	s_lshl_b64 s[0:1], s[46:47], 2
	s_add_u32 s0, s4, s0
	s_addc_u32 s1, s5, s1
	v_writelane_b32 v234, s0, 36
	s_ashr_i32 s11, s10, 31
	s_nop 0
	v_writelane_b32 v234, s1, 37
	s_mul_i32 s0, s63, s62
	s_mul_i32 s0, s0, s33
	v_writelane_b32 v234, s0, 38
	v_writelane_b32 v234, s8, 39
	s_lshr_b32 s0, s8, 31
	v_writelane_b32 v234, s0, 40
	s_add_i32 s0, s9, s10
	v_writelane_b32 v234, s0, 41
	s_lshl_b64 s[0:1], s[10:11], 2
	v_writelane_b32 v234, s0, 42
	s_mov_b32 s33, 0xf800000
	s_nop 0
	v_writelane_b32 v234, s1, 43
	s_lshl_b64 s[0:1], s[10:11], 11
	v_writelane_b32 v234, s0, 44
	s_nop 1
	v_writelane_b32 v234, s1, 45
	s_add_u32 s0, s68, 0x800
	v_writelane_b32 v234, s0, 46
	v_writelane_b32 v234, s68, 47
	s_addc_u32 s0, s69, 0
	s_nop 0
	v_writelane_b32 v234, s69, 48
	v_writelane_b32 v234, s70, 49
	v_writelane_b32 v234, s71, 50
	v_writelane_b32 v234, s72, 51
	v_writelane_b32 v234, s73, 52
	v_writelane_b32 v234, s74, 53
	v_writelane_b32 v234, s75, 54
	v_writelane_b32 v234, s76, 55
	v_writelane_b32 v234, s77, 56
	v_writelane_b32 v234, s78, 57
	v_writelane_b32 v234, s79, 58
	v_writelane_b32 v234, s80, 59
	v_writelane_b32 v234, s81, 60
	v_writelane_b32 v234, s82, 61
	v_writelane_b32 v234, s83, 62
	v_writelane_b32 v234, s0, 63
	s_lshl_b64 s[0:1], s[10:11], 12
	v_writelane_b32 v233, s0, 0
	s_mov_b32 s70, s9
	s_mov_b64 s[68:69], s[10:11]
	v_writelane_b32 v233, s1, 1
	s_add_u32 s0, s60, 0xb300080
	v_writelane_b32 v233, s0, 2
	s_addc_u32 s0, s61, 0
	v_writelane_b32 v233, s0, 3
	s_add_u32 s0, s60, 0x9320000
	s_mov_b64 s[4:5], s[56:57]
	v_writelane_b32 v233, s0, 4
	s_mov_b64 s[6:7], s[58:59]
	s_mov_b64 s[8:9], s[60:61]
	s_mov_b32 s10, s62
	v_writelane_b32 v233, s4, 5
	s_addc_u32 s0, s61, 0
	s_ashr_i32 s65, s64, 31
	v_writelane_b32 v233, s5, 6
	v_writelane_b32 v233, s6, 7
	v_writelane_b32 v233, s7, 8
	v_writelane_b32 v233, s8, 9
	v_writelane_b32 v233, s9, 10
	v_writelane_b32 v233, s10, 11
	v_writelane_b32 v233, s11, 12
	v_writelane_b32 v233, s0, 13
	s_lshl_b32 s0, s64, 2
	v_writelane_b32 v233, s0, 14
	s_lshl_b32 s0, s64, 9
	v_writelane_b32 v233, s0, 15
	s_add_i32 s0, 0, 0x20040
	v_writelane_b32 v233, s0, 16
	s_add_i32 s0, 0, 0x20044
	v_writelane_b32 v233, s0, 17
	s_lshl_b64 s[8:9], s[64:65], 2
	v_writelane_b32 v233, s8, 18
	s_mov_b32 s1, 0
	s_mov_b32 s0, s68
	v_writelane_b32 v233, s9, 19
	s_lshl_b64 s[8:9], s[64:65], 11
	v_writelane_b32 v233, s8, 20
	s_mov_b64 s[76:77], s[16:17]
	s_mov_b64 s[78:79], s[18:19]
	v_writelane_b32 v233, s9, 21
	s_lshl_b64 s[8:9], s[64:65], 12
	v_writelane_b32 v233, s8, 22
	s_mov_b64 s[82:83], s[22:23]
	s_mov_b32 s6, 0x41b00000
	v_writelane_b32 v233, s9, 23
	s_lshl_b64 s[8:9], s[64:65], 6
	v_writelane_b32 v233, s8, 24
	s_mov_b32 s18, 0x42580000
	s_mov_b32 s22, 0x42500000
	v_writelane_b32 v233, s9, 25
	v_writelane_b32 v233, s86, 26
	s_mov_b32 s4, 0x42100000
	s_mov_b32 s10, 0x42080000
	v_writelane_b32 v233, s87, 27
	v_writelane_b32 v233, s98, 28
	v_writelane_b32 v233, s0, 29
	s_mov_b32 s7, 0x41b80000
	s_mov_b32 s19, 0x425c0000
	v_writelane_b32 v233, s1, 30
	s_mov_b32 s0, s64
	v_writelane_b32 v233, s0, 31
	s_mov_b32 s23, 0x42540000
	s_mov_b32 s5, 0x42140000
	v_writelane_b32 v233, s1, 32
	v_writelane_b32 v233, s99, 33
	v_writelane_b32 v233, s70, 34
	v_writelane_b32 v233, s50, 35
	s_mov_b32 s11, 0x420c0000
	s_movk_i32 s81, 0x7fff
	v_writelane_b32 v233, s51, 36
	v_writelane_b32 v233, s52, 37
	s_mov_b32 s71, 0xffff0000
	s_movk_i32 s80, 0x48
	v_writelane_b32 v233, s53, 38
	v_writelane_b32 v233, s54, 39
	s_mov_b64 s[16:17], 0x20000
	s_nop 0
	v_writelane_b32 v233, s55, 40
	v_writelane_b32 v233, s66, 41
	s_nop 1
	v_writelane_b32 v233, s67, 42
	v_writelane_b32 v233, s76, 43
	s_nop 1
	v_writelane_b32 v233, s77, 44
	v_writelane_b32 v233, s78, 45
	s_nop 1
	v_writelane_b32 v233, s79, 46
	v_writelane_b32 v233, s82, 47
	s_nop 1
	v_writelane_b32 v233, s83, 48
	s_mov_b32 s0, 0
	v_writelane_b32 v232, s0, 58
	v_writelane_b32 v232, s0, 59
	s_branch .LBB0_31

.LBB0_320:
	s_andn2_b64 vcc, exec, s[0:1]
	s_cbranch_vccnz .LBB0_399
	v_bfe_i32 v2, v12, 27, 1
	v_lshlrev_b32_e32 v0, 4, v12
	v_lshrrev_b32_e32 v2, 22, v2
	v_add_u32_e32 v2, v0, v2
	v_and_b32_e32 v2, 0xfffffc00, v2
	v_sub_u32_e32 v2, v0, v2
	v_ashrrev_i32_e32 v1, 31, v12
	s_waitcnt lgkmcnt(0)
	v_lshrrev_b32_e32 v3, 4, v2
	v_lshrrev_b32_e32 v1, 26, v1
	v_bitop3_b32 v2, v3, v2, 32 bitop3:0x6c
	v_add_u32_e32 v1, v12, v1
	v_ashrrev_i32_e32 v4, 31, v2
	v_ashrrev_i32_e32 v1, 6, v1
	v_lshrrev_b32_e32 v4, 26, v4
	v_lshlrev_b32_e32 v3, 3, v1
	v_add_u32_e32 v4, v2, v4
	v_and_b32_e32 v3, -16, v3
	v_ashrrev_i32_e32 v5, 6, v4
	v_lshlrev_b32_e32 v1, 5, v1
	v_add_u32_e32 v3, v5, v3
	v_and_b32_e32 v13, 32, v1
	v_and_b32_e32 v1, 0xc0, v4
	v_sub_u32_e32 v1, v2, v1
	v_lshlrev_b32_e32 v2, 1, v3
	v_lshrrev_b32_e32 v4, 2, v3
	v_and_b32_e32 v5, 3, v5
	s_mov_b32 s1, 0x7fffffe0
	v_ashrrev_i16_sdwa v1, v155, sext(v1) dst_sel:DWORD dst_unused:UNUSED_PAD src0_sel:DWORD src1_sel:BYTE_0
	v_and_b32_e32 v2, 24, v2
	v_and_b32_e32 v4, 4, v4
	v_and_or_b32 v5, v3, s1, v5
	v_bfe_i32 v14, v1, 0, 16
	v_or3_b32 v2, v5, v4, v2
	v_readlane_b32 s52, v233, 50
	v_add_u32_e32 v1, v13, v14
	v_add_u32_e32 v0, 0x2000, v0
	v_mul_lo_u32 v15, v3, s52
	v_mul_lo_u32 v2, v2, s52
	v_add_lshl_u32 v130, v1, v15, 1
	v_add_lshl_u32 v96, v2, v1, 1
	v_ashrrev_i32_e32 v1, 31, v0
	v_lshrrev_b32_e32 v1, 22, v1
	v_add_u32_e32 v1, v0, v1
	v_ashrrev_i32_e32 v1, 10, v1
	v_readlane_b32 s53, v233, 51
	v_mul_i32_i24_e32 v2, 0x400, v1
	v_sub_u32_e32 v0, v0, v2
	s_mov_b32 s53, s47
	v_lshrrev_b32_e32 v2, 4, v0
	s_lshl_b64 s[72:73], s[52:53], 9
	s_ashr_i32 s9, s46, 31
	v_bitop3_b32 v0, v2, v0, 32 bitop3:0x6c
	s_mul_i32 s9, s72, s9
	s_mul_hi_u32 s39, s72, s46
	v_ashrrev_i32_e32 v3, 31, v0
	s_add_i32 s9, s39, s9
	s_lshr_b32 s39, s52, 23
	v_writelane_b32 v232, s76, 22
	v_lshrrev_b32_e32 v3, 26, v3
	s_mul_i32 s40, s39, s46
	v_writelane_b32 v232, s77, 23
	v_lshlrev_b32_e32 v2, 3, v1
	v_add_u32_e32 v3, v0, v3
	s_add_i32 s43, s9, s40
	s_ashr_i32 s9, s69, 31
	v_writelane_b32 v232, s78, 24
	v_and_b32_e32 v2, -16, v2
	v_ashrrev_i32_e32 v4, 6, v3
	s_mul_i32 s9, s72, s9
	s_mul_hi_u32 s40, s72, s69
	v_writelane_b32 v232, s79, 25
	s_ashr_i32 s0, s38, 6
	v_add_u32_e32 v2, v4, v2
	v_lshlrev_b32_e32 v1, 5, v1
	v_and_b32_e32 v4, 3, v4
	s_add_i32 s9, s40, s9
	s_mul_i32 s39, s39, s69
	v_and_b32_e32 v16, 32, v1
	v_and_b32_e32 v1, 0xc0, v3
	v_and_or_b32 v4, v2, s1, v4
	s_ashr_i32 s1, s38, 8
	s_lshl_b64 s[34:35], s[52:53], 8
	s_lshl_b32 s8, s0, 10
	s_add_i32 s9, s9, s39
	s_mul_i32 s39, s72, s69
	v_readlane_b32 s40, v232, 11
	v_sub_u32_e32 v0, v0, v1
	v_lshlrev_b32_e32 v1, 1, v2
	v_lshrrev_b32_e32 v3, 2, v2
	v_readlane_b32 s41, v232, 12
	s_add_u32 s78, s40, s39
	v_ashrrev_i16_sdwa v0, v155, sext(v0) dst_sel:DWORD dst_unused:UNUSED_PAD src0_sel:DWORD src1_sel:BYTE_0
	v_and_b32_e32 v1, 24, v1
	v_and_b32_e32 v3, 4, v3
	s_addc_u32 s79, s41, s9
	s_add_i32 s9, s8, 0
	v_bfe_i32 v17, v0, 0, 16
	v_or3_b32 v1, v4, v3, v1
	v_readlane_b32 vcc_lo, v232, 58
	s_cmp_eq_u32 vcc_lo, 0
	s_cbranch_scc1 .Lsb_done_g
	v_readfirstlane_b32 vcc_hi, v152
	s_cmp_lt_u32 vcc_hi, 64
	s_cbranch_scc0 .Lsb_wait_g
	v_readlane_b32 s100, v234, 34
	v_readlane_b32 s101, v234, 35
	v_readlane_b32 vcc_lo, v232, 59
	s_lshl_b32 vcc_lo, vcc_lo, 5
	v_mov_b32_e32 v211, vcc_lo
	s_mov_b32 m0, 0
	s_nop 4
.Lsb_poll_g:
	global_load_dword v210, v97, s[100:101] sc1
	s_waitcnt vmcnt(0)
	v_cmp_lt_u32_e32 vcc, v210, v211
	s_cbranch_vccz .Lsb_got_g
	s_sleep 1
	s_add_u32 m0, m0, 1
	s_cmp_lt_u32 m0, 0x40000
	s_cbranch_scc1 .Lsb_poll_g
.Lsb_got_g:
	buffer_inv sc1
	s_waitcnt vmcnt(0)
.Lsb_wait_g:
	s_mov_b32 vcc_lo, 0
	v_writelane_b32 v232, vcc_lo, 58
	s_barrier
.Lsb_done_g:
	s_add_i32 m0, s9, 0x10000
	v_add_u32_e32 v0, v16, v17
	v_mul_lo_u32 v1, v1, s52
	global_load_lds_dwordx4 v96, s[78:79]
	s_add_i32 m0, s9, 0x12000
	v_add_lshl_u32 v134, v1, v0, 1
	s_add_u32 s40, s78, s34
	global_load_lds_dwordx4 v134, s[78:79]
	s_addc_u32 s41, s79, s35
	s_add_i32 m0, s9, 0x14000
	s_mul_i32 s42, s72, s46
	global_load_lds_dwordx4 v96, s[40:41]
	s_add_i32 m0, s9, 0x16000
	v_readlane_b32 s48, v232, 4
	v_readlane_b32 s49, v232, 5
	s_add_u32 s42, s48, s42
	s_addc_u32 s43, s49, s43
	s_add_i32 s98, s9, 0x2000
	v_mul_lo_u32 v18, v2, s52
	global_load_lds_dwordx4 v134, s[40:41]
	s_mov_b32 m0, s9
	s_add_u32 s48, s42, s34
	v_add_lshl_u32 v132, v0, v18, 1
	global_load_lds_dwordx4 v130, s[42:43]
	s_mov_b32 m0, s98
	s_addc_u32 s49, s43, s35
	s_add_i32 s99, s9, 0x4000
	global_load_lds_dwordx4 v132, s[42:43]
	s_mov_b32 m0, s99
	s_add_i32 s76, s9, 0x6000
	global_load_lds_dwordx4 v130, s[48:49]
	s_mov_b32 m0, s76
	v_mov_b32_e32 v135, v97
	global_load_lds_dwordx4 v132, s[48:49]
	s_cmp_eq_u32 s1, 1
	v_lshl_add_u64 v[2:3], s[40:41], 0, v[96:97]
	v_lshl_add_u64 v[0:1], s[40:41], 0, v[134:135]
	v_mov_b32_e32 v131, v97
	v_mov_b32_e32 v133, v97
	s_cselect_b64 s[40:41], -1, 0
	v_lshl_add_u64 v[8:9], s[78:79], 0, v[96:97]
	v_lshl_add_u64 v[4:5], s[78:79], 0, v[134:135]
	v_lshl_add_u64 v[6:7], s[42:43], 0, v[130:131]
	v_writelane_b32 v232, s40, 6
	s_cmp_lg_u32 s1, 1
	v_lshl_add_u64 v[10:11], s[42:43], 0, v[132:133]
	v_writelane_b32 v232, s41, 7
	s_cbranch_scc1 .LBB0_323
	s_barrier

.LBB0_486:
	s_and_b64 vcc, exec, s[0:1]
	s_cbranch_vccz .LBB0_511
	v_readlane_b32 s0, v235, 30
	v_readlane_b32 s1, v232, 21
	s_add_i32 s8, s0, s1
	v_readlane_b32 s0, v236, 8
	v_readlane_b32 s1, v236, 9
	s_and_b64 s[0:1], s[0:1], exec
	s_cselect_b32 s8, s8, s76
	s_cmp_ge_i32 s8, s98
	s_cbranch_scc1 .LBB0_511
	v_readlane_b32 vcc_lo, v232, 58
	s_cmp_eq_u32 vcc_lo, 0
	s_cbranch_scc1 .Lsb_done_r
	v_readfirstlane_b32 vcc_hi, v152
	s_cmp_lt_u32 vcc_hi, 64
	s_cbranch_scc0 .Lsb_wait_r
	v_readlane_b32 s100, v234, 34
	v_readlane_b32 s101, v234, 35
	v_readlane_b32 vcc_lo, v232, 59
	s_lshl_b32 vcc_lo, vcc_lo, 5
	v_mov_b32_e32 v211, vcc_lo
	s_mov_b32 m0, 0
	s_nop 4

.Lsb_done_r:
	v_lshlrev_b32_e32 v48, 4, v159
	s_waitcnt lgkmcnt(0)
	global_load_dwordx4 v[0:3], v48, s[78:79]
	global_load_dwordx4 v[4:7], v48, s[78:79] offset:1024
	global_load_dwordx4 v[8:11], v48, s[78:79] offset:2048
	global_load_dwordx4 v[12:15], v48, s[78:79] offset:3072
	v_readlane_b32 s56, v233, 60
	v_readlane_b32 s57, v233, 61
	s_cmp_eq_u64 s[56:57], 0
	s_cselect_b64 s[38:39], -1, 0
	s_cmp_lg_u64 s[56:57], 0
	s_cselect_b64 s[34:35], -1, 0
	s_ashr_i32 s9, s8, 31
	s_mov_b64 s[40:41], -1
	s_and_b64 vcc, exec, s[38:39]
	s_cbranch_vccnz .LBB0_490
	s_lshl_b64 s[0:1], s[8:9], 12
	s_add_u32 s0, s56, s0
	s_addc_u32 s1, s57, s1
	global_load_dwordx4 v[44:47], v48, s[0:1]
	global_load_dwordx4 v[36:39], v48, s[0:1] offset:1024
	global_load_dwordx4 v[24:27], v48, s[0:1] offset:2048
	global_load_dwordx4 v[16:19], v48, s[0:1] offset:3072
	s_lshl_b64 s[0:1], s[8:9], 11
	s_mov_b64 s[40:41], 0

.LBB0_511:
	v_readlane_b32 vcc_lo, v232, 58
	s_cmp_eq_u32 vcc_lo, 0
	s_cbranch_scc1 .Lsb_done_e
	v_readfirstlane_b32 vcc_hi, v152
	s_cmp_lt_u32 vcc_hi, 64
	s_cbranch_scc0 .Lsb_wait_e
	v_readlane_b32 s100, v234, 34
	v_readlane_b32 s101, v234, 35
	v_readlane_b32 vcc_lo, v232, 59
	s_lshl_b32 vcc_lo, vcc_lo, 5
	v_mov_b32_e32 v211, vcc_lo
	s_mov_b32 m0, 0
	s_nop 4

.LBB0_566:
	v_readlane_b32 s8, v232, 13
	v_readlane_b32 s9, v232, 14
	s_and_b64 vcc, exec, s[8:9]
	s_cbranch_vccz .LBB0_586
	s_waitcnt vmcnt(0)
	s_waitcnt vmcnt(0) lgkmcnt(0)
	s_barrier
	s_and_saveexec_b64 s[0:1], s[86:87]
	s_cbranch_execz .LBB0_585
	s_mov_b64 s[34:35], exec
	v_mbcnt_lo_u32_b32 v0, s34, 0
	v_mbcnt_hi_u32_b32 v0, s35, v0
	v_cmp_eq_u32_e32 vcc, 0, v0
	s_and_saveexec_b64 s[8:9], vcc
	s_cbranch_execz .LBB0_570
	s_bcnt1_i32_b64 s34, s[34:35]
	v_mov_b32_e32 v1, s34
	v_readlane_b32 s34, v234, 34
	v_readlane_b32 s35, v234, 35
	s_nop 4
	global_atomic_add v97, v1, s[34:35]
.LBB0_570:
	s_or_b64 exec, exec, s[8:9]
	s_branch .LBB0_585
	s_waitcnt vmcnt(0)
	v_readfirstlane_b32 s8, v1
	s_mov_b64 s[34:35], -1
	s_nop 0
	v_add_u32_e32 v2, s8, v0
	v_readlane_b32 s8, v234, 36
	v_and_b32_e32 v0, 31, v2
	v_readlane_b32 s9, v234, 37
	v_cmp_ne_u32_e32 vcc, 31, v0
	s_nop 0
	v_mov_b64_e32 v[0:1], s[8:9]
	s_and_saveexec_b64 s[8:9], vcc
	s_cbranch_execz .LBB0_582
	v_readlane_b32 s34, v234, 34
	v_readlane_b32 s35, v234, 35
	v_or_b32_e32 v0, 31, v2
	v_add_u32_e32 v0, 1, v0
	s_mov_b64 s[38:39], 0
	s_nop 2
	global_load_dword v1, v97, s[34:35] sc1
	s_waitcnt vmcnt(0)
	v_cmp_lt_u32_e32 vcc, v1, v0
	s_and_saveexec_b64 s[34:35], vcc
	s_cbranch_execz .LBB0_581
	s_mov_b32 s46, 1
	s_branch .LBB0_574

.LBB0_585:
	s_or_b64 exec, exec, s[0:1]
	v_readlane_b32 s8, v232, 59
	s_add_i32 s8, s8, 1
	v_writelane_b32 v232, s8, 59
	s_mov_b32 s8, 1
	v_writelane_b32 v232, s8, 58
	s_mov_b64 s[0:1], -1

	.amdhsa_kernel _Z8mega_fwd6Params
		.amdhsa_group_segment_fixed_size 0
		.amdhsa_private_segment_fixed_size 0
		.amdhsa_kernarg_size 376
		.amdhsa_user_sgpr_count 2
		.amdhsa_user_sgpr_dispatch_ptr 0
		.amdhsa_user_sgpr_queue_ptr 0
		.amdhsa_user_sgpr_kernarg_segment_ptr 1
		.amdhsa_user_sgpr_dispatch_id 0
		.amdhsa_user_sgpr_kernarg_preload_length 0
		.amdhsa_user_sgpr_kernarg_preload_offset 0
		.amdhsa_user_sgpr_private_segment_size 0
		.amdhsa_uses_dynamic_stack 0
		.amdhsa_enable_private_segment 0
		.amdhsa_system_sgpr_workgroup_id_x 1
		.amdhsa_system_sgpr_workgroup_id_y 0
		.amdhsa_system_sgpr_workgroup_id_z 0
		.amdhsa_system_sgpr_workgroup_info 0
		.amdhsa_system_vgpr_workitem_id 2
		.amdhsa_next_free_vgpr 237
		.amdhsa_next_free_sgpr 102
		.amdhsa_accum_offset 240
		.amdhsa_reserve_vcc 1
		.amdhsa_float_round_mode_32 0
		.amdhsa_float_round_mode_16_64 0
		.amdhsa_float_denorm_mode_32 3
		.amdhsa_float_denorm_mode_16_64 3
		.amdhsa_dx10_clamp 1
		.amdhsa_ieee_mode 1
		.amdhsa_fp16_overflow 0
		.amdhsa_tg_split 0
		.amdhsa_exception_fp_ieee_invalid_op 0
		.amdhsa_exception_fp_denorm_src 0
		.amdhsa_exception_fp_ieee_div_zero 0
		.amdhsa_exception_fp_ieee_overflow 0
		.amdhsa_exception_fp_ieee_underflow 0
		.amdhsa_exception_fp_ieee_inexact 0
		.amdhsa_exception_int_div_zero 0
	.end_amdhsa_kernel

amdhsa.kernels:
  - .agpr_count:     0
    .args:
      - .offset:         0
        .size:           120
        .value_kind:     by_value
      - .offset:         120
        .size:           4
        .value_kind:     hidden_block_count_x
      - .offset:         124
        .size:           4
        .value_kind:     hidden_block_count_y
      - .offset:         128
        .size:           4
        .value_kind:     hidden_block_count_z
      - .offset:         132
        .size:           2
        .value_kind:     hidden_group_size_x
      - .offset:         134
        .size:           2
        .value_kind:     hidden_group_size_y
      - .offset:         136
        .size:           2
        .value_kind:     hidden_group_size_z
      - .offset:         138
        .size:           2
        .value_kind:     hidden_remainder_x
      - .offset:         140
        .size:           2
        .value_kind:     hidden_remainder_y
      - .offset:         142
        .size:           2
        .value_kind:     hidden_remainder_z
      - .offset:         160
        .size:           8
        .value_kind:     hidden_global_offset_x
      - .offset:         168
        .size:           8
        .value_kind:     hidden_global_offset_y
      - .offset:         176
        .size:           8
        .value_kind:     hidden_global_offset_z
      - .offset:         184
        .size:           2
        .value_kind:     hidden_grid_dims
      - .offset:         208
        .size:           8
        .value_kind:     hidden_multigrid_sync_arg
      - .offset:         240
        .size:           4
        .value_kind:     hidden_dynamic_lds_size
    .group_segment_fixed_size: 0
    .kernarg_segment_align: 8
    .kernarg_segment_size: 376
    .language:       OpenCL C
    .language_version:
      - 2
      - 0
    .max_flat_workgroup_size: 512
    .name:           _Z8mega_fwd6Params
    .private_segment_fixed_size: 0
    .sgpr_count:     108
    .sgpr_spill_count: 634
    .symbol:         _Z8mega_fwd6Params.kd
    .uniform_work_group_size: 1
    .uses_dynamic_stack: false
    .vgpr_count:     237
    .vgpr_spill_count: 0
    .wavefront_size: 64
